# v34 plus attention second-half K/V loads unconditional and the over-draining vmcnt(0) before the LDS writes removed (vmcnt(4) is exact)
# baseline (speedup 1.0000x reference)
; __device__ __forceinline__ void partialSM(f32x16& p0, f32x16& p1, float& m_reg, float& mn, float& alpha) {
;   constexpr float C = SCALE * 1.4426950408889634f;
;   float pmax = p0[0];
; #pragma unroll
;   for (int r = 1; r < 16; ++r) pmax = fmaxf(pmax, p0[r]);
; #pragma unroll
;   for (int r = 0; r < 16; ++r) pmax = fmaxf(pmax, p1[r]);
;   { auto rr = __builtin_amdgcn_permlane32_swap(__float_as_uint(pmax), __float_as_uint(pmax), false, false);
;     pmax = fmaxf(__uint_as_float(rr[0]), __uint_as_float(rr[1])); }
;   if (__builtin_expect(__all(pmax - m_reg <= THR / SCALE), 1)) { mn = m_reg; alpha = 1.f; }
;   else { mn = fmaxf(m_reg, pmax); alpha = __builtin_amdgcn_exp2f((m_reg - mn) * C); m_reg = mn; }
;   float mnC = -mn * C;
; #pragma unroll
;   for (int r = 0; r < 16; ++r) p0[r] = fmaf(p0[r], C, mnC);
; #pragma unroll
;   for (int r = 0; r < 16; ++r) p1[r] = fmaf(p1[r], C, mnC);
; #pragma unroll
;   for (int r = 0; r < 16; ++r) p0[r] = __builtin_amdgcn_exp2f(p0[r]);
; }
; __device__ __forceinline__ void finishSM(f32x16& p0, f32x16& p1, float alpha, float& l_reg, bf16x8& pa0, bf16x8& pa1, bf16x8& pa2, bf16x8& pa3) {
; #pragma unroll
;   for (int r = 0; r < 16; ++r) p1[r] = __builtin_amdgcn_exp2f(p1[r]);
;   float ps = 0;
; #pragma unroll
;   for (int r = 0; r < 16; ++r) ps += p0[r];
; #pragma unroll
;   for (int r = 0; r < 16; ++r) ps += p1[r];
;   { auto rr = __builtin_amdgcn_permlane32_swap(__float_as_uint(ps), __float_as_uint(ps), false, false);
;     ps = __uint_as_float(rr[0]) + __uint_as_float(rr[1]); }
;   l_reg = l_reg * alpha + ps;
;     ...
;   PK4(p0, 0, pa0); PK4(p0, 8, pa1); PK4(p1, 0, pa2); PK4(p1, 8, pa3);
;     ...
; }
; __device__ __forceinline__ void qkt(f32x16& p0, f32x16& p1, const bf16_t* Ks, const bf16x8* qr, int r32, int hi) {
;   p0 = f32x16{}; p1 = f32x16{};
; #pragma unroll
;   for (int d0 = 0; d0 < 8; ++d0) { int cb = (d0 * 16 + hi * 8) * 2;
;     bf16x8 b0 = *reinterpret_cast<const bf16x8*>((const char*)Ks + KSWZ(r32, cb));
;     bf16x8 b1 = *reinterpret_cast<const bf16x8*>((const char*)Ks + KSWZ(32 + r32, cb));
;     p0 = __builtin_amdgcn_mfma_f32_32x32x16_bf16(b0, qr[d0], p0, 0, 0, 0);
;     p1 = __builtin_amdgcn_mfma_f32_32x32x16_bf16(b1, qr[d0], p1, 0, 0, 0); }
.LBB0_203:
	v_cndmask_b32_e64 v218, v162, v170, s[0:1]
	v_mul_f32_e32 v219, 0xbe0293ee, v218
	v_fmamk_f32 v80, v80, 0x3e0293ee, v219
	v_fmamk_f32 v81, v81, 0x3e0293ee, v219
	v_fmamk_f32 v82, v82, 0x3e0293ee, v219
	v_fmamk_f32 v83, v83, 0x3e0293ee, v219
	v_fmamk_f32 v84, v84, 0x3e0293ee, v219
	v_fmamk_f32 v85, v85, 0x3e0293ee, v219
	v_fmamk_f32 v86, v86, 0x3e0293ee, v219
	v_fmamk_f32 v87, v87, 0x3e0293ee, v219
	v_fmamk_f32 v88, v88, 0x3e0293ee, v219
	v_fmamk_f32 v89, v89, 0x3e0293ee, v219
	v_fmamk_f32 v90, v90, 0x3e0293ee, v219
	v_fmamk_f32 v91, v91, 0x3e0293ee, v219
	v_fmamk_f32 v92, v92, 0x3e0293ee, v219
	v_fmamk_f32 v93, v93, 0x3e0293ee, v219
	v_fmamk_f32 v94, v94, 0x3e0293ee, v219
	v_fmamk_f32 v95, v95, 0x3e0293ee, v219
	v_exp_f32_e32 v162, v80
	v_exp_f32_e32 v177, v81
	v_exp_f32_e32 v163, v82
	v_exp_f32_e32 v176, v83
	v_exp_f32_e32 v164, v84
	v_exp_f32_e32 v175, v85
	v_exp_f32_e32 v165, v86
	v_exp_f32_e32 v174, v87
	v_exp_f32_e32 v166, v88
	v_exp_f32_e32 v173, v89
	v_exp_f32_e32 v167, v90
	v_exp_f32_e32 v172, v91
	v_exp_f32_e32 v168, v92
	v_exp_f32_e32 v171, v93
	v_exp_f32_e32 v169, v94
	v_exp_f32_e32 v170, v95
	v_fmamk_f32 v228, v64, 0x3e0293ee, v219
	v_fmamk_f32 v229, v65, 0x3e0293ee, v219
	v_fmamk_f32 v230, v66, 0x3e0293ee, v219
	v_fmamk_f32 v231, v67, 0x3e0293ee, v219
	v_fmamk_f32 v232, v68, 0x3e0293ee, v219
	v_fmamk_f32 v221, v69, 0x3e0293ee, v219
	v_fmamk_f32 v222, v70, 0x3e0293ee, v219
	v_fmamk_f32 v223, v71, 0x3e0293ee, v219
	v_fmamk_f32 v224, v72, 0x3e0293ee, v219
	v_fmamk_f32 v225, v73, 0x3e0293ee, v219
	v_fmamk_f32 v226, v74, 0x3e0293ee, v219
	v_fmamk_f32 v227, v75, 0x3e0293ee, v219
	v_fmamk_f32 v220, v76, 0x3e0293ee, v219
	v_fmamk_f32 v233, v77, 0x3e0293ee, v219
	v_fmamk_f32 v234, v78, 0x3e0293ee, v219
	v_fmac_f32_e32 v219, 0x3e0293ee, v79
	s_waitcnt lgkmcnt(0)
	s_barrier
	ds_read_b128 v[64:67], v206 offset:32768
	ds_read_b128 v[68:71], v206 offset:40960
	ds_read_b128 v[236:239], v211 offset:32768
	ds_read_b128 v[240:243], v211 offset:40960
	v_exp_f32_e32 v228, v228
	v_exp_f32_e32 v229, v229
	s_waitcnt lgkmcnt(0)
	v_mfma_f32_32x32x16_bf16 v[80:95], v[64:67], v[118:121], 0
	v_exp_f32_e32 v230, v230
	v_exp_f32_e32 v231, v231
	v_exp_f32_e32 v232, v232
	v_exp_f32_e32 v221, v221
	v_exp_f32_e32 v222, v222
	v_exp_f32_e32 v223, v223
	v_exp_f32_e32 v224, v224
	v_mfma_f32_32x32x16_bf16 v[64:79], v[68:71], v[118:121], 0
	v_exp_f32_e32 v225, v225
	v_exp_f32_e32 v226, v226
	v_exp_f32_e32 v227, v227
	v_exp_f32_e32 v235, v220
	v_exp_f32_e32 v233, v233
	v_exp_f32_e32 v234, v234
	v_mfma_f32_32x32x16_bf16 v[80:95], v[236:239], v[114:117], v[80:95]
	v_mfma_f32_32x32x16_bf16 v[64:79], v[240:243], v[114:117], v[64:79]
	ds_read_b128 v[236:239], v210 offset:32768
	ds_read_b128 v[240:243], v210 offset:40960
	s_waitcnt lgkmcnt(0)
	v_mfma_f32_32x32x16_bf16 v[80:95], v[236:239], v[126:129], v[80:95]
	v_mfma_f32_32x32x16_bf16 v[64:79], v[240:243], v[126:129], v[64:79]
	ds_read_b128 v[236:239], v209 offset:32768
	ds_read_b128 v[240:243], v209 offset:40960
	s_waitcnt lgkmcnt(0)
	v_mfma_f32_32x32x16_bf16 v[80:95], v[236:239], v[122:125], v[80:95]
	v_mfma_f32_32x32x16_bf16 v[64:79], v[240:243], v[122:125], v[64:79]
	ds_read_b128 v[236:239], v208 offset:32768
	ds_read_b128 v[240:243], v208 offset:40960
	s_waitcnt lgkmcnt(0)
	v_mfma_f32_32x32x16_bf16 v[80:95], v[236:239], v[110:113], v[80:95]
	v_mfma_f32_32x32x16_bf16 v[64:79], v[240:243], v[110:113], v[64:79]
	ds_read_b128 v[236:239], v207 offset:32768
	ds_read_b128 v[240:243], v207 offset:40960
	s_waitcnt lgkmcnt(0)
	v_mfma_f32_32x32x16_bf16 v[80:95], v[236:239], v[106:109], v[80:95]
	v_mfma_f32_32x32x16_bf16 v[64:79], v[240:243], v[106:109], v[64:79]
	ds_read_b128 v[236:239], v213 offset:32768
	ds_read_b128 v[240:243], v213 offset:40960
	s_waitcnt lgkmcnt(0)
	v_mfma_f32_32x32x16_bf16 v[80:95], v[236:239], v[102:105], v[80:95]
	v_mfma_f32_32x32x16_bf16 v[64:79], v[240:243], v[102:105], v[64:79]
	ds_read_b128 v[236:239], v212 offset:32768
	ds_read_b128 v[240:243], v212 offset:40960
	s_waitcnt lgkmcnt(0)
	v_mfma_f32_32x32x16_bf16 v[80:95], v[236:239], v[98:101], v[80:95]
	v_exp_f32_e32 v236, v219
	v_add_f32_e32 v219, 0, v162
	v_add_f32_e32 v219, v177, v219
	v_add_f32_e32 v219, v163, v219
	v_add_f32_e32 v219, v176, v219
	v_add_f32_e32 v219, v164, v219
	v_add_f32_e32 v219, v175, v219
	v_add_f32_e32 v219, v165, v219
	v_add_f32_e32 v219, v174, v219
	v_add_f32_e32 v219, v166, v219
	v_add_f32_e32 v219, v173, v219
	v_add_f32_e32 v219, v167, v219
	v_add_f32_e32 v219, v172, v219
	v_add_f32_e32 v219, v168, v219
	v_add_f32_e32 v219, v171, v219
	v_add_f32_e32 v219, v169, v219
	v_add_f32_e32 v219, v170, v219
	v_add_f32_e32 v219, v228, v219
	v_add_f32_e32 v219, v229, v219
	v_add_f32_e32 v219, v230, v219
	v_add_f32_e32 v219, v231, v219
	v_add_f32_e32 v219, v232, v219
	v_add_f32_e32 v219, v221, v219
	v_add_f32_e32 v219, v222, v219
	v_add_f32_e32 v219, v223, v219
	v_add_f32_e32 v219, v224, v219
	v_add_f32_e32 v219, v225, v219
	v_mfma_f32_32x32x16_bf16 v[64:79], v[240:243], v[98:101], v[64:79]
	s_cmp_ge_u32 s30, s29
	s_cselect_b64 s[22:23], -1, 0
	s_and_b64 vcc, exec, s[22:23]
	v_add_co_u32_e32 v130, vcc, 0x48888000, v188
	s_nop 1
	v_addc_co_u32_e32 v131, vcc, 0, v189, vcc
	v_add_co_u32_e32 v134, vcc, 0x48888000, v186
	s_nop 1
	v_addc_co_u32_e32 v135, vcc, 0, v187, vcc
	v_add_co_u32_e32 v138, vcc, 0x48048000, v188
	s_nop 1
	v_addc_co_u32_e32 v139, vcc, 0, v189, vcc
	v_add_co_u32_e32 v142, vcc, 0x48048000, v186
	s_nop 1
	v_addc_co_u32_e32 v143, vcc, 0, v187, vcc
; __device__ __forceinline__ void finishSM(f32x16& p0, f32x16& p1, float alpha, float& l_reg, bf16x8& pa0, bf16x8& pa1, bf16x8& pa2, bf16x8& pa3) {
; #pragma unroll
;   for (int r = 0; r < 16; ++r) p1[r] = __builtin_amdgcn_exp2f(p1[r]);
;   float ps = 0;
; #pragma unroll
;   for (int r = 0; r < 16; ++r) ps += p0[r];
; #pragma unroll
;   for (int r = 0; r < 16; ++r) ps += p1[r];
;   { auto rr = __builtin_amdgcn_permlane32_swap(__float_as_uint(ps), __float_as_uint(ps), false, false);
;     ps = __uint_as_float(rr[0]) + __uint_as_float(rr[1]); }
;   l_reg = l_reg * alpha + ps;
;     ...
;   PK4(p0, 0, pa0); PK4(p0, 8, pa1); PK4(p1, 0, pa2); PK4(p1, 8, pa3);
;     ...
; }
.Lap_skipaddr:
	v_add_f32_e32 v219, v226, v219
	v_add_f32_e32 v219, v227, v219
	v_add_f32_e32 v219, v235, v219
	v_add_f32_e32 v219, v233, v219
	v_add_f32_e32 v219, v234, v219
	v_add_f32_e32 v219, v236, v219
	v_mov_b32_e32 v220, v219
	v_cvt_pk_bf16_f32 v162, v162, v177
	v_cvt_pk_bf16_f32 v163, v163, v176
	v_cvt_pk_bf16_f32 v164, v164, v175
	v_cvt_pk_bf16_f32 v165, v165, v174
	v_cvt_pk_bf16_f32 v166, v166, v173
	v_cvt_pk_bf16_f32 v167, v167, v172
	v_cvt_pk_bf16_f32 v168, v168, v171
	v_cvt_pk_bf16_f32 v169, v169, v170
	v_cvt_pk_bf16_f32 v170, v228, v229
	v_cvt_pk_bf16_f32 v171, v230, v231
	v_cvt_pk_bf16_f32 v172, v232, v221
	v_cvt_pk_bf16_f32 v173, v222, v223
	v_cvt_pk_bf16_f32 v174, v224, v225
	v_cvt_pk_bf16_f32 v175, v226, v227
	v_cvt_pk_bf16_f32 v176, v235, v233
	v_cvt_pk_bf16_f32 v177, v234, v236
	ds_read_b64_tr_b16 v[186:187], v200 offset:0
	ds_read_b64_tr_b16 v[188:189], v200 offset:0x800
	ds_read_b64_tr_b16 v[222:223], v200 offset:0x1000
	ds_read_b64_tr_b16 v[224:225], v200 offset:0x1800
	ds_read_b64_tr_b16 v[226:227], v200 offset:0x2000
	ds_read_b64_tr_b16 v[228:229], v200 offset:0x2800
	ds_read_b64_tr_b16 v[230:231], v200 offset:0x3000
	ds_read_b64_tr_b16 v[232:233], v200 offset:0x3800
	s_nop 1
	v_permlane32_swap_b32_e32 v219, v220
	v_permlane32_swap_b32_e32 v162, v164
	v_permlane32_swap_b32_e32 v163, v165
	v_permlane32_swap_b32_e32 v166, v168
	v_permlane32_swap_b32_e32 v167, v169
	v_permlane32_swap_b32_e32 v170, v172
	v_permlane32_swap_b32_e32 v171, v173
	v_permlane32_swap_b32_e32 v174, v176
	v_permlane32_swap_b32_e32 v175, v177
	s_and_b64 vcc, exec, s[22:23]
	global_load_dwordx4 v[130:133], v[130:131], off
	s_nop 0
	global_load_dwordx4 v[134:137], v[134:135], off
	global_load_dwordx4 v[138:141], v[138:139], off
	s_nop 0
	global_load_dwordx4 v[142:145], v[142:143], off
; #define SBAR() __builtin_amdgcn_sched_barrier(0)
; #define SWRITE(b, i) do { *(bf16x8*)((char*)V_lds + (b) * SHM_V + vst0) = sr_[i].vs0;          \
;     *(bf16x8*)((char*)V_lds + (b) * SHM_V + vst1) = sr_[i].vs1; int kc = sc * 2;               \
;     *(bf16x8*)((char*)K_lds + (b) * SHM_K + KSWZ(sr, kc)) = sr_[i].ks0;                       \
;     *(bf16x8*)((char*)K_lds + (b) * SHM_K + KSWZ(32 + sr, kc)) = sr_[i].ks1; } while (0)
; template <int D0> __device__ __forceinline__ void pv_one(f32x16& od, int vb, bf16x8 pa0, bf16x8 pa1, bf16x8 pa2, bf16x8 pa3) {
;   const s16x4 l0 = tr_read<v_rd_off(D0, 0, 0)>(vb), h0 = tr_read<v_rd_off(D0, 0, 1)>(vb), l1 = tr_read<v_rd_off(D0, 1, 0)>(vb), h1 = tr_read<v_rd_off(D0, 1, 1)>(vb);
;   const s16x4 l2 = tr_read<v_rd_off(D0, 2, 0)>(vb), h2 = tr_read<v_rd_off(D0, 2, 1)>(vb), l3 = tr_read<v_rd_off(D0, 3, 0)>(vb), h3 = tr_read<v_rd_off(D0, 3, 1)>(vb);
;   asm volatile("s_waitcnt lgkmcnt(0)" ::: "memory"); SBAR();
;     ...
;   od = __builtin_amdgcn_mfma_f32_32x32x16_bf16(pa0, PK(l0, h0), od, 0, 0, 0);
;   od = __builtin_amdgcn_mfma_f32_32x32x16_bf16(pa1, PK(l1, h1), od, 0, 0, 0);
;   od = __builtin_amdgcn_mfma_f32_32x32x16_bf16(pa2, PK(l2, h2), od, 0, 0, 0);
;   od = __builtin_amdgcn_mfma_f32_32x32x16_bf16(pa3, PK(l3, h3), od, 0, 0, 0);
;     ...
; }
; __device__ __forceinline__ void pv_d0(f32x16* o, int vb, bf16x8 pa0, bf16x8 pa1, bf16x8 pa2, bf16x8 pa3) {
;   pv_one<0>(o[0], vb, pa0, pa1, pa2, pa3); pv_one<1>(o[1], vb, pa0, pa1, pa2, pa3); pv_one<2>(o[2], vb, pa0, pa1, pa2, pa3); pv_one<3>(o[3], vb, pa0, pa1, pa2, pa3);
; }
; __device__ __forceinline__ void attn_body(const bf16_t* __restrict__ Qb, const bf16_t* __restrict__ Kh, const bf16_t* __restrict__ Vh,
;                                           bf16_t* __restrict__ Ob, const bf16_t* __restrict__ AGb, int seq, char* lds) {
;     ...
;     pv_d0(o, vb0, pa0, pa1, pa2, pa3); partialSM(pB0, pB1, m_reg, mnB, alB);
;     __syncthreads(); SWAIT(); SWRITE(0, SE);
;     RESC(alB); __syncthreads();
;     SBAR(); qkt(pA0, pA1, K_lds, qr, r32, hi);
;     finishSM(pB0, pB1, alB, l_reg, pa0, pa1, pa2, pa3); SBAR();
;     if (j + 3 < NT) SLOAD(SE, (j + 3) * KVBLK); SBAR();
;     pv_d0(o, vb0 + (int)SHM_V, pa0, pa1, pa2, pa3); partialSM(pA0, pA1, m_reg, mnA, alA);
;     __syncthreads(); SWAIT(); SWRITE(1, SO);
;     RESC(alA); __syncthreads();
.LBB0_205:
	s_waitcnt lgkmcnt(0)
	s_nop 0
	v_mfma_f32_32x32x16_bf16 v[0:15], v[162:165], v[186:189], v[0:15]
	ds_read_b64_tr_b16 v[186:187], v200 offset:0x200
	ds_read_b64_tr_b16 v[188:189], v200 offset:0xa00
	v_mfma_f32_32x32x16_bf16 v[0:15], v[166:169], v[222:225], v[0:15]
	ds_read_b64_tr_b16 v[222:223], v200 offset:0x1200
	ds_read_b64_tr_b16 v[224:225], v200 offset:0x1a00
	v_mfma_f32_32x32x16_bf16 v[0:15], v[170:173], v[226:229], v[0:15]
	ds_read_b64_tr_b16 v[226:227], v200 offset:0x2200
	ds_read_b64_tr_b16 v[228:229], v200 offset:0x2a00
	v_mfma_f32_32x32x16_bf16 v[0:15], v[174:177], v[230:233], v[0:15]
	ds_read_b64_tr_b16 v[230:231], v200 offset:0x3200
	ds_read_b64_tr_b16 v[232:233], v200 offset:0x3a00
	s_waitcnt lgkmcnt(0)
	v_mfma_f32_32x32x16_bf16 v[48:63], v[162:165], v[186:189], v[48:63]
	ds_read_b64_tr_b16 v[186:187], v200 offset:0x400
	ds_read_b64_tr_b16 v[188:189], v200 offset:0xc00
	v_mfma_f32_32x32x16_bf16 v[48:63], v[166:169], v[222:225], v[48:63]
	ds_read_b64_tr_b16 v[222:223], v200 offset:0x1400
	ds_read_b64_tr_b16 v[224:225], v200 offset:0x1c00
	v_mfma_f32_32x32x16_bf16 v[48:63], v[170:173], v[226:229], v[48:63]
	ds_read_b64_tr_b16 v[226:227], v200 offset:0x2400
	ds_read_b64_tr_b16 v[228:229], v200 offset:0x2c00
	v_mfma_f32_32x32x16_bf16 v[48:63], v[174:177], v[230:233], v[48:63]
	ds_read_b64_tr_b16 v[230:231], v200 offset:0x3400
	ds_read_b64_tr_b16 v[232:233], v200 offset:0x3c00
	s_waitcnt lgkmcnt(0)
	v_mfma_f32_32x32x16_bf16 v[32:47], v[162:165], v[186:189], v[32:47]
	ds_read_b64_tr_b16 v[186:187], v200 offset:0x600
	ds_read_b64_tr_b16 v[188:189], v200 offset:0xe00
	v_mfma_f32_32x32x16_bf16 v[32:47], v[166:169], v[222:225], v[32:47]
	ds_read_b64_tr_b16 v[222:223], v200 offset:0x1600
	ds_read_b64_tr_b16 v[224:225], v200 offset:0x1e00
	v_mfma_f32_32x32x16_bf16 v[32:47], v[170:173], v[226:229], v[32:47]
	ds_read_b64_tr_b16 v[226:227], v200 offset:0x2600
	ds_read_b64_tr_b16 v[228:229], v200 offset:0x2e00
	v_mfma_f32_32x32x16_bf16 v[32:47], v[174:177], v[230:233], v[32:47]
	ds_read_b64_tr_b16 v[230:231], v200 offset:0x3600
	ds_read_b64_tr_b16 v[232:233], v200 offset:0x3e00
	s_waitcnt lgkmcnt(0)
	v_mfma_f32_32x32x16_bf16 v[16:31], v[162:165], v[186:189], v[16:31]
	v_max_f32_e32 v162, v81, v81
	v_max_f32_e32 v163, v80, v80
	v_max_f32_e32 v162, v163, v162
	v_max3_f32 v162, v162, v82, v83
	v_max3_f32 v162, v162, v84, v85
	v_max3_f32 v162, v162, v86, v87
	v_max3_f32 v162, v162, v88, v89
	v_max3_f32 v162, v162, v90, v91
	v_max3_f32 v162, v162, v92, v93
	v_mfma_f32_32x32x16_bf16 v[16:31], v[166:169], v[222:225], v[16:31]
	v_max3_f32 v162, v162, v94, v95
	v_max3_f32 v162, v162, v64, v65
	v_max3_f32 v162, v162, v66, v67
	v_max3_f32 v162, v162, v68, v69
	v_max3_f32 v162, v162, v70, v71
	v_max3_f32 v162, v162, v72, v73
	v_max3_f32 v162, v162, v74, v75
	v_max3_f32 v162, v162, v76, v77
	v_mfma_f32_32x32x16_bf16 v[16:31], v[170:173], v[226:229], v[16:31]
	v_max3_f32 v162, v162, v78, v79
	v_mov_b32_e32 v163, v162
	s_nop 1
	v_permlane32_swap_b32_e32 v162, v163
	v_max_f32_e32 v163, v163, v163
	v_max_f32_e32 v162, v162, v162
	v_max_f32_e32 v162, v162, v163
	v_sub_f32_e32 v163, v162, v218
	v_cmp_ge_f32_e32 vcc, s62, v163
	v_max_f32_e32 v163, v218, v218
	v_max_f32_e32 v163, v163, v162
	v_mfma_f32_32x32x16_bf16 v[16:31], v[174:177], v[230:233], v[16:31]
	v_sub_f32_e32 v162, v218, v163
	v_mul_f32_e32 v162, 0x3e0293ee, v162
	v_exp_f32_e32 v162, v162
	s_cmp_eq_u64 vcc, exec
	s_cselect_b64 s[0:1], -1, 0
	s_waitcnt lgkmcnt(0)
	s_barrier
	s_waitcnt vmcnt(4)
	v_cndmask_b32_e64 v162, v162, 1.0, s[0:1]
	v_cmp_gt_f32_e32 vcc, 1.0, v162
	ds_write_b128 v204, v[146:149] offset:16384
	ds_write_b128 v205, v[150:153] offset:16384
	ds_write_b128 v202, v[154:157] offset:49152
	ds_write_b128 v203, v[158:161] offset:49152
	s_cbranch_vccz .LBB0_209
	s_and_saveexec_b64 s[24:25], s[4:5]
	ds_write_b32 v183, v162 offset:128
	s_or_b64 exec, exec, s[24:25]
	s_waitcnt lgkmcnt(0)
	v_add_u32_e32 v158, v181, v180
	ds_read_b128 v[146:149], v158 offset:224
	ds_read_b128 v[150:153], v158 offset:192
	ds_read_b128 v[154:157], v158 offset:160
	ds_read_b128 v[158:161], v158 offset:128
	s_waitcnt lgkmcnt(3)
	v_pk_mul_f32 v[12:13], v[12:13], v[146:147]
	s_waitcnt lgkmcnt(2)
	v_pk_mul_f32 v[8:9], v[8:9], v[150:151]
	s_waitcnt lgkmcnt(1)
	v_pk_mul_f32 v[4:5], v[4:5], v[154:155]
	v_pk_mul_f32 v[14:15], v[14:15], v[148:149]
	v_pk_mul_f32 v[10:11], v[10:11], v[152:153]
	v_pk_mul_f32 v[6:7], v[6:7], v[156:157]
	s_waitcnt lgkmcnt(0)
	v_pk_mul_f32 v[2:3], v[2:3], v[160:161]
	v_pk_mul_f32 v[0:1], v[0:1], v[158:159]
	v_pk_mul_f32 v[60:61], v[60:61], v[146:147]
	v_pk_mul_f32 v[56:57], v[56:57], v[150:151]
	v_pk_mul_f32 v[52:53], v[52:53], v[154:155]
	v_pk_mul_f32 v[62:63], v[62:63], v[148:149]
	v_pk_mul_f32 v[58:59], v[58:59], v[152:153]
	v_pk_mul_f32 v[54:55], v[54:55], v[156:157]
	v_pk_mul_f32 v[50:51], v[50:51], v[160:161]
	v_pk_mul_f32 v[48:49], v[48:49], v[158:159]
	v_pk_mul_f32 v[44:45], v[44:45], v[146:147]
	v_pk_mul_f32 v[40:41], v[40:41], v[150:151]
	v_pk_mul_f32 v[36:37], v[36:37], v[154:155]
	v_pk_mul_f32 v[46:47], v[46:47], v[148:149]
	v_pk_mul_f32 v[42:43], v[42:43], v[152:153]
	v_pk_mul_f32 v[38:39], v[38:39], v[156:157]
	v_pk_mul_f32 v[34:35], v[34:35], v[160:161]
	v_pk_mul_f32 v[32:33], v[32:33], v[158:159]
	v_pk_mul_f32 v[28:29], v[28:29], v[146:147]
	v_pk_mul_f32 v[24:25], v[24:25], v[150:151]
	v_pk_mul_f32 v[20:21], v[20:21], v[154:155]
	v_pk_mul_f32 v[30:31], v[30:31], v[148:149]
	v_pk_mul_f32 v[26:27], v[26:27], v[152:153]
	v_pk_mul_f32 v[22:23], v[22:23], v[156:157]
	v_pk_mul_f32 v[18:19], v[18:19], v[160:161]
	v_pk_mul_f32 v[16:17], v[16:17], v[158:159]

; #define SBAR() __builtin_amdgcn_sched_barrier(0)
; __device__ __forceinline__ void qkt(f32x16& p0, f32x16& p1, const bf16_t* Ks, const bf16x8* qr, int r32, int hi) {
;   p0 = f32x16{}; p1 = f32x16{};
; #pragma unroll
;   for (int d0 = 0; d0 < 8; ++d0) { int cb = (d0 * 16 + hi * 8) * 2;
;     bf16x8 b0 = *reinterpret_cast<const bf16x8*>((const char*)Ks + KSWZ(r32, cb));
;     bf16x8 b1 = *reinterpret_cast<const bf16x8*>((const char*)Ks + KSWZ(32 + r32, cb));
;     p0 = __builtin_amdgcn_mfma_f32_32x32x16_bf16(b0, qr[d0], p0, 0, 0, 0);
;     p1 = __builtin_amdgcn_mfma_f32_32x32x16_bf16(b1, qr[d0], p1, 0, 0, 0); }
; __device__ __forceinline__ void attn_body(const bf16_t* __restrict__ Qb, const bf16_t* __restrict__ Kh, const bf16_t* __restrict__ Vh,
;                                           bf16_t* __restrict__ Ob, const bf16_t* __restrict__ AGb, int seq, char* lds) {
;     ...
;   SBAR(); qkt(pB0, pB1, (bf16_t*)((char*)K_lds + SHM_K), qr, r32, hi);
;   finishSM(pA0, pA1, alA, l_reg, pa0, pa1, pa2, pa3); SBAR();
;   pv_d0(o, vb0, pa0, pa1, pa2, pa3); partialSM(pB0, pB1, m_reg, mnB, alB);
.LBB0_211:
	s_waitcnt vmcnt(0)
	ds_read_b128 v[64:67], v206 offset:49152
	ds_read_b128 v[68:71], v206 offset:57344
	v_add_f32_e32 v96, 0, v163
	v_add_f32_e32 v96, v177, v96
	v_add_f32_e32 v96, v164, v96
	s_waitcnt lgkmcnt(1)
	v_mfma_f32_32x32x16_bf16 v[80:95], v[64:67], v[118:121], 0
	v_add_f32_e32 v96, v186, v96
	v_add_f32_e32 v96, v176, v96
	v_add_f32_e32 v96, v187, v96
	v_add_f32_e32 v96, v165, v96
	v_add_f32_e32 v96, v175, v96
	v_add_f32_e32 v96, v166, v96
	v_add_f32_e32 v96, v173, v96
	s_waitcnt lgkmcnt(0)
	v_mfma_f32_32x32x16_bf16 v[64:79], v[68:71], v[118:121], 0
	ds_read_b128 v[118:121], v211 offset:49152
	ds_read_b128 v[130:133], v211 offset:57344
	v_add_f32_e32 v96, v167, v96
	v_add_f32_e32 v96, v174, v96
	v_add_f32_e32 v96, v168, v96
	v_add_f32_e32 v96, v171, v96
	v_add_f32_e32 v96, v169, v96
	v_add_f32_e32 v96, v172, v96
	s_waitcnt lgkmcnt(1)
	v_mfma_f32_32x32x16_bf16 v[80:95], v[118:121], v[114:117], v[80:95]
	s_waitcnt lgkmcnt(0)
	v_mfma_f32_32x32x16_bf16 v[64:79], v[130:133], v[114:117], v[64:79]
	ds_read_b128 v[114:117], v210 offset:49152
	ds_read_b128 v[118:121], v210 offset:57344
	s_waitcnt lgkmcnt(1)
	v_mfma_f32_32x32x16_bf16 v[80:95], v[114:117], v[126:129], v[80:95]
	s_waitcnt lgkmcnt(0)
	v_mfma_f32_32x32x16_bf16 v[64:79], v[118:121], v[126:129], v[64:79]
	ds_read_b128 v[114:117], v209 offset:49152
	ds_read_b128 v[118:121], v209 offset:57344
	s_waitcnt lgkmcnt(1)
	v_mfma_f32_32x32x16_bf16 v[80:95], v[114:117], v[122:125], v[80:95]
	s_waitcnt lgkmcnt(0)
	v_mfma_f32_32x32x16_bf16 v[64:79], v[118:121], v[122:125], v[64:79]
	ds_read_b128 v[114:117], v208 offset:49152
	ds_read_b128 v[118:121], v208 offset:57344
	v_exp_f32_e32 v122, v147
	s_waitcnt lgkmcnt(1)
	v_mfma_f32_32x32x16_bf16 v[80:95], v[114:117], v[110:113], v[80:95]
	s_waitcnt lgkmcnt(0)
	v_mfma_f32_32x32x16_bf16 v[64:79], v[118:121], v[110:113], v[64:79]
	ds_read_b128 v[110:113], v207 offset:49152
	ds_read_b128 v[114:117], v207 offset:57344
	v_exp_f32_e32 v118, v157
	v_exp_f32_e32 v119, v152
	v_exp_f32_e32 v120, v153
	v_exp_f32_e32 v121, v146
	s_waitcnt lgkmcnt(1)
	v_mfma_f32_32x32x16_bf16 v[80:95], v[110:113], v[106:109], v[80:95]
	s_waitcnt lgkmcnt(0)
	v_mfma_f32_32x32x16_bf16 v[64:79], v[114:117], v[106:109], v[64:79]
	ds_read_b128 v[106:109], v213 offset:49152
	ds_read_b128 v[110:113], v213 offset:57344
	v_exp_f32_e32 v114, v151
	v_exp_f32_e32 v115, v148
	v_exp_f32_e32 v116, v149
	v_exp_f32_e32 v117, v156
	s_waitcnt lgkmcnt(1)
	v_mfma_f32_32x32x16_bf16 v[80:95], v[106:109], v[102:105], v[80:95]
	s_waitcnt lgkmcnt(0)
	v_mfma_f32_32x32x16_bf16 v[64:79], v[110:113], v[102:105], v[64:79]
	ds_read_b128 v[102:105], v212 offset:49152
	ds_read_b128 v[106:109], v212 offset:57344
	v_exp_f32_e32 v110, v159
	v_exp_f32_e32 v111, v154
	v_exp_f32_e32 v112, v155
	v_exp_f32_e32 v113, v150
	s_waitcnt lgkmcnt(1)
	v_mfma_f32_32x32x16_bf16 v[80:95], v[102:105], v[98:101], v[80:95]
	v_exp_f32_e32 v103, v160
	s_nop 0
	v_add_f32_e32 v96, v103, v96
	s_waitcnt lgkmcnt(0)
	v_mfma_f32_32x32x16_bf16 v[64:79], v[106:109], v[98:101], v[64:79]
	v_exp_f32_e32 v108, v161
	v_exp_f32_e32 v109, v158
	v_cvt_pk_bf16_f32 v98, v163, v177
	v_cvt_pk_bf16_f32 v99, v164, v186
	v_add_f32_e32 v96, v108, v96
	v_add_f32_e32 v96, v109, v96
	v_add_f32_e32 v96, v110, v96
	v_add_f32_e32 v96, v111, v96
	v_add_f32_e32 v96, v112, v96
	v_add_f32_e32 v96, v113, v96
	v_add_f32_e32 v96, v114, v96
	v_add_f32_e32 v96, v115, v96
	v_add_f32_e32 v96, v116, v96
	v_add_f32_e32 v96, v117, v96
	v_add_f32_e32 v96, v118, v96
	v_add_f32_e32 v96, v119, v96
	v_add_f32_e32 v96, v120, v96
	v_add_f32_e32 v96, v121, v96
	v_add_f32_e32 v96, v122, v96
	v_mov_b32_e32 v102, v96
	v_cvt_pk_bf16_f32 v100, v176, v187
	v_cvt_pk_bf16_f32 v101, v165, v175
	s_nop 1
	v_permlane32_swap_b32_e32 v96, v102
	v_permlane32_swap_b32_e32 v98, v100
	v_permlane32_swap_b32_e32 v99, v101
	v_cvt_pk_bf16_f32 v104, v166, v173
	v_cvt_pk_bf16_f32 v105, v167, v174
	v_cvt_pk_bf16_f32 v106, v168, v171
	v_cvt_pk_bf16_f32 v107, v169, v172
	v_cvt_pk_bf16_f32 v108, v103, v108
	v_cvt_pk_bf16_f32 v109, v109, v110
	v_cvt_pk_bf16_f32 v110, v111, v112
	v_cvt_pk_bf16_f32 v111, v113, v114
	v_cvt_pk_bf16_f32 v112, v115, v116
	v_cvt_pk_bf16_f32 v113, v117, v118
	v_cvt_pk_bf16_f32 v114, v119, v120
	v_cvt_pk_bf16_f32 v115, v121, v122
	s_nop 0
	v_permlane32_swap_b32_e32 v104, v106
	v_permlane32_swap_b32_e32 v105, v107
	v_permlane32_swap_b32_e32 v108, v110
	v_permlane32_swap_b32_e32 v109, v111
	v_permlane32_swap_b32_e32 v112, v114
	v_permlane32_swap_b32_e32 v113, v115
	ds_read_b64_tr_b16 v[116:117], v201 offset:0
	ds_read_b64_tr_b16 v[118:119], v201 offset:0x800
	ds_read_b64_tr_b16 v[120:121], v201 offset:0x1000
	ds_read_b64_tr_b16 v[122:123], v201 offset:0x1800
	ds_read_b64_tr_b16 v[124:125], v201 offset:0x2000
	ds_read_b64_tr_b16 v[126:127], v201 offset:0x2800
	ds_read_b64_tr_b16 v[128:129], v201 offset:0x3000
	ds_read_b64_tr_b16 v[130:131], v201 offset:0x3800
	s_waitcnt lgkmcnt(0)
; #define SBAR() __builtin_amdgcn_sched_barrier(0)
; #define RESC(a) do { if (__any((a) < 1.f)) { if (hi == 0) al_l[r32] = (a); asm volatile("s_waitcnt lgkmcnt(0)" ::: "memory"); \
;     _Pragma("unroll") for (int d = 0; d < 4; ++d) _Pragma("unroll") for (int r = 0; r < 16; ++r) o[d][r] *= al_l[crow(r, hi)]; } } while (0)
; template <int D0> __device__ __forceinline__ void pv_one(f32x16& od, int vb, bf16x8 pa0, bf16x8 pa1, bf16x8 pa2, bf16x8 pa3) {
;   const s16x4 l0 = tr_read<v_rd_off(D0, 0, 0)>(vb), h0 = tr_read<v_rd_off(D0, 0, 1)>(vb), l1 = tr_read<v_rd_off(D0, 1, 0)>(vb), h1 = tr_read<v_rd_off(D0, 1, 1)>(vb);
;   const s16x4 l2 = tr_read<v_rd_off(D0, 2, 0)>(vb), h2 = tr_read<v_rd_off(D0, 2, 1)>(vb), l3 = tr_read<v_rd_off(D0, 3, 0)>(vb), h3 = tr_read<v_rd_off(D0, 3, 1)>(vb);
;   asm volatile("s_waitcnt lgkmcnt(0)" ::: "memory"); SBAR();
;     ...
;   od = __builtin_amdgcn_mfma_f32_32x32x16_bf16(pa0, PK(l0, h0), od, 0, 0, 0);
;   od = __builtin_amdgcn_mfma_f32_32x32x16_bf16(pa1, PK(l1, h1), od, 0, 0, 0);
;   od = __builtin_amdgcn_mfma_f32_32x32x16_bf16(pa2, PK(l2, h2), od, 0, 0, 0);
;   od = __builtin_amdgcn_mfma_f32_32x32x16_bf16(pa3, PK(l3, h3), od, 0, 0, 0);
;     ...
; }
; __device__ __forceinline__ void pv_d0(f32x16* o, int vb, bf16x8 pa0, bf16x8 pa1, bf16x8 pa2, bf16x8 pa3) {
;   pv_one<0>(o[0], vb, pa0, pa1, pa2, pa3); pv_one<1>(o[1], vb, pa0, pa1, pa2, pa3); pv_one<2>(o[2], vb, pa0, pa1, pa2, pa3); pv_one<3>(o[3], vb, pa0, pa1, pa2, pa3);
; }
; __device__ __forceinline__ void attn_body(const bf16_t* __restrict__ Qb, const bf16_t* __restrict__ Kh, const bf16_t* __restrict__ Vh,
;                                           bf16_t* __restrict__ Ob, const bf16_t* __restrict__ AGb, int seq, char* lds) {
;     ...
;   pv_d0(o, vb0, pa0, pa1, pa2, pa3); partialSM(pB0, pB1, m_reg, mnB, alB);
;   __syncthreads(); RESC(alB);
	s_nop 0
	v_mfma_f32_32x32x16_bf16 v[0:15], v[98:101], v[116:119], v[0:15]
	ds_read_b64_tr_b16 v[116:117], v201 offset:0x200
	ds_read_b64_tr_b16 v[118:119], v201 offset:0xa00
	v_mfma_f32_32x32x16_bf16 v[0:15], v[104:107], v[120:123], v[0:15]
	ds_read_b64_tr_b16 v[120:121], v201 offset:0x1200
	ds_read_b64_tr_b16 v[122:123], v201 offset:0x1a00
	v_mfma_f32_32x32x16_bf16 v[0:15], v[108:111], v[124:127], v[0:15]
	ds_read_b64_tr_b16 v[124:125], v201 offset:0x2200
	ds_read_b64_tr_b16 v[126:127], v201 offset:0x2a00
	v_mfma_f32_32x32x16_bf16 v[0:15], v[112:115], v[128:131], v[0:15]
	ds_read_b64_tr_b16 v[128:129], v201 offset:0x3200
	ds_read_b64_tr_b16 v[130:131], v201 offset:0x3a00
	s_waitcnt lgkmcnt(0)
	v_mfma_f32_32x32x16_bf16 v[48:63], v[98:101], v[116:119], v[48:63]
	ds_read_b64_tr_b16 v[116:117], v201 offset:0x400
	ds_read_b64_tr_b16 v[118:119], v201 offset:0xc00
	v_mfma_f32_32x32x16_bf16 v[48:63], v[104:107], v[120:123], v[48:63]
	ds_read_b64_tr_b16 v[120:121], v201 offset:0x1400
	ds_read_b64_tr_b16 v[122:123], v201 offset:0x1c00
	v_mfma_f32_32x32x16_bf16 v[48:63], v[108:111], v[124:127], v[48:63]
	ds_read_b64_tr_b16 v[124:125], v201 offset:0x2400
	ds_read_b64_tr_b16 v[126:127], v201 offset:0x2c00
	v_mfma_f32_32x32x16_bf16 v[48:63], v[112:115], v[128:131], v[48:63]
	ds_read_b64_tr_b16 v[128:129], v201 offset:0x3400
	ds_read_b64_tr_b16 v[130:131], v201 offset:0x3c00
	s_waitcnt lgkmcnt(0)
	v_mfma_f32_32x32x16_bf16 v[32:47], v[98:101], v[116:119], v[32:47]
	ds_read_b64_tr_b16 v[116:117], v201 offset:0x600
	ds_read_b64_tr_b16 v[118:119], v201 offset:0xe00
	v_mfma_f32_32x32x16_bf16 v[32:47], v[104:107], v[120:123], v[32:47]
	ds_read_b64_tr_b16 v[120:121], v201 offset:0x1600
	ds_read_b64_tr_b16 v[122:123], v201 offset:0x1e00
	v_mfma_f32_32x32x16_bf16 v[32:47], v[108:111], v[124:127], v[32:47]
	ds_read_b64_tr_b16 v[124:125], v201 offset:0x2600
	ds_read_b64_tr_b16 v[126:127], v201 offset:0x2e00
	v_mfma_f32_32x32x16_bf16 v[32:47], v[112:115], v[128:131], v[32:47]
	ds_read_b64_tr_b16 v[128:129], v201 offset:0x3600
	ds_read_b64_tr_b16 v[130:131], v201 offset:0x3e00
	s_waitcnt lgkmcnt(0)
	v_mfma_f32_32x32x16_bf16 v[16:31], v[98:101], v[116:119], v[16:31]
	v_max_f32_e32 v98, v81, v81
	v_max_f32_e32 v99, v80, v80
	v_max_f32_e32 v98, v99, v98
	v_max3_f32 v98, v98, v82, v83
	v_max3_f32 v98, v98, v84, v85
	v_max3_f32 v98, v98, v86, v87
	v_max3_f32 v98, v98, v88, v89
	v_max3_f32 v98, v98, v90, v91
	v_max3_f32 v98, v98, v92, v93
	v_mfma_f32_32x32x16_bf16 v[16:31], v[104:107], v[120:123], v[16:31]
	v_max3_f32 v98, v98, v94, v95
	v_max3_f32 v98, v98, v64, v65
	v_max3_f32 v98, v98, v66, v67
	v_max3_f32 v98, v98, v68, v69
	v_max3_f32 v98, v98, v70, v71
	v_max3_f32 v98, v98, v72, v73
	v_max3_f32 v98, v98, v74, v75
	v_max3_f32 v98, v98, v76, v77
	v_mfma_f32_32x32x16_bf16 v[16:31], v[108:111], v[124:127], v[16:31]
	v_max3_f32 v98, v98, v78, v79
	v_mov_b32_e32 v99, v98
	s_nop 1
	v_permlane32_swap_b32_e32 v98, v99
	v_max_f32_e32 v99, v99, v99
	v_max_f32_e32 v98, v98, v98
	v_max_f32_e32 v98, v98, v99
	v_sub_f32_e32 v99, v98, v170
	v_cmp_ge_f32_e32 vcc, s62, v99
	v_max_f32_e32 v99, v170, v170
	v_max_f32_e32 v99, v99, v98
	v_mfma_f32_32x32x16_bf16 v[16:31], v[112:115], v[128:131], v[16:31]
	v_sub_f32_e32 v98, v170, v99
	v_mul_f32_e32 v98, 0x3e0293ee, v98
	v_exp_f32_e32 v98, v98
	s_cmp_eq_u64 vcc, exec
	s_cselect_b64 s[0:1], -1, 0
	v_cndmask_b32_e64 v98, v98, 1.0, s[0:1]
	v_cmp_gt_f32_e32 vcc, 1.0, v98
	s_barrier
	s_cbranch_vccz .LBB0_215
	s_and_saveexec_b64 s[20:21], s[4:5]
	ds_write_b32 v183, v98 offset:128
	s_or_b64 exec, exec, s[20:21]
	s_waitcnt lgkmcnt(0)
	v_add_u32_e32 v100, v181, v180
	ds_read_b128 v[104:107], v100 offset:224
	ds_read_b128 v[108:111], v100 offset:192
	ds_read_b128 v[112:115], v100 offset:160
	ds_read_b128 v[116:119], v100 offset:128
	s_waitcnt lgkmcnt(3)
	v_pk_mul_f32 v[12:13], v[12:13], v[104:105]
	s_waitcnt lgkmcnt(2)
	v_pk_mul_f32 v[8:9], v[8:9], v[108:109]
	s_waitcnt lgkmcnt(1)
	v_pk_mul_f32 v[4:5], v[4:5], v[112:113]
	v_pk_mul_f32 v[14:15], v[14:15], v[106:107]
	v_pk_mul_f32 v[10:11], v[10:11], v[110:111]
	v_pk_mul_f32 v[6:7], v[6:7], v[114:115]
	s_waitcnt lgkmcnt(0)
	v_pk_mul_f32 v[2:3], v[2:3], v[118:119]
	v_pk_mul_f32 v[0:1], v[0:1], v[116:117]
	v_pk_mul_f32 v[60:61], v[60:61], v[104:105]
	v_pk_mul_f32 v[56:57], v[56:57], v[108:109]
	v_pk_mul_f32 v[52:53], v[52:53], v[112:113]
	v_pk_mul_f32 v[62:63], v[62:63], v[106:107]
	v_pk_mul_f32 v[58:59], v[58:59], v[110:111]
	v_pk_mul_f32 v[54:55], v[54:55], v[114:115]
	v_pk_mul_f32 v[50:51], v[50:51], v[118:119]
	v_pk_mul_f32 v[48:49], v[48:49], v[116:117]
	v_pk_mul_f32 v[44:45], v[44:45], v[104:105]
	v_pk_mul_f32 v[40:41], v[40:41], v[108:109]
	v_pk_mul_f32 v[36:37], v[36:37], v[112:113]
	v_pk_mul_f32 v[46:47], v[46:47], v[106:107]
	v_pk_mul_f32 v[42:43], v[42:43], v[110:111]
	v_pk_mul_f32 v[38:39], v[38:39], v[114:115]
	v_pk_mul_f32 v[34:35], v[34:35], v[118:119]
	v_pk_mul_f32 v[32:33], v[32:33], v[116:117]
	v_pk_mul_f32 v[28:29], v[28:29], v[104:105]
	v_pk_mul_f32 v[24:25], v[24:25], v[108:109]
	v_pk_mul_f32 v[20:21], v[20:21], v[112:113]
	v_pk_mul_f32 v[30:31], v[30:31], v[106:107]
	v_pk_mul_f32 v[26:27], v[26:27], v[110:111]
	v_pk_mul_f32 v[22:23], v[22:23], v[114:115]
	v_pk_mul_f32 v[18:19], v[18:19], v[118:119]
	v_pk_mul_f32 v[16:17], v[16:17], v[116:117]
